# ph3 reorder for half the blocks + scan2 rewritten with two elements per lane and scalar pointer walking
# speedup vs baseline: 1.0051x; 1.0051x over previous
; __device__ __forceinline__ void ph_scan2(const P& p) {
;     ...
;   int gt = (blockIdx.x + zz) * NTHR + (threadIdx.x + zz), gs = (gridDim.x + zz) * NTHR;
;   const int NG = 64 * 2048, NS = 64 * 8192;
;   for (int i = gt; i < NG + NS + NG; i += gs) {
;     int m, rem;
;     if (i < NG) { m = 0; rem = i; } else if (i < NG + NS) { m = 1; rem = i - NG; } else { m = 2; rem = i - NG - NS; }
;     int dk = m == 1 ? 128 : 32; int g = m == 0 ? 32 : 1;
;     size_t so = m == 0 ? SLOC_G : (m == 1 ? SLOC_S : SLOC_R);
;     size_t dof = m == 0 ? DEC_G : (m == 1 ? DEC_S : DEC_R);
;     int esz = dk * 64;
;     int seq = rem / esz, e = rem - seq * esz;
;     int dir = seq & 1;
;     int kk = e & (dk - 1);
;     int gi = g > 1 ? kk : 0;
;     float run = 0.f;
; #pragma unroll 1
;     for (int s0 = 0; s0 < 36; s0 += 18) {
;       float loc[18], dd[18]; size_t aa[18];
; #pragma unroll
;       for (int u = 0; u < 18; u++) {
;         int s = s0 + u;
;         int gc = dir == 0 ? s : (s < 4 ? 3 - s : 39 - s);
;         aa[u] = so + ((size_t)seq * 36 + gc) * esz + e;
;         loc[u] = SLOC[aa[u]];
;         dd[u] = DEC[dof + ((size_t)seq * 36 + gc) * g + gi];
;       }
.Lro_scan2:
	s_mov_b32 s0, 0
	s_ashr_i32 s1, s0, 31
	s_add_u32 s0, s88, s0
	s_addc_u32 s1, s89, s1
	s_load_dwordx2 s[2:3], s[0:1], 0x118
	s_mov_b32 s0, 0
	s_mov_b64 s[6:7], exec
	s_waitcnt lgkmcnt(0)
	s_add_u32 s8, s2, 0x23ad9000
	s_addc_u32 s9, s3, 0
	s_add_u32 s10, s2, 0x2a725800
	s_addc_u32 s11, s3, 0
	s_add_u32 s12, s2, 0x2a6d9000
	s_addc_u32 s13, s3, 0
	v_lshrrev_b32_e32 v0, 6, v128
	v_lshlrev_b32_e32 v2, 3, v212
	v_lshlrev_b32_e32 v3, 2, v212
	v_readfirstlane_b32 s4, v0
	v_and_b32_e32 v9, 15, v212
	v_lshlrev_b32_e32 v9, 3, v9
	v_add_u32_e32 v1, 4, v9
	s_lshl_b32 s5, s87, 8
	s_lshl_b32 s4, s4, 6
	s_add_i32 s14, s5, s4
	s_lshl_b32 s15, s90, 8
.Ls2_iter:
	s_cmp_ge_u32 s14, 0x60000
	s_cbranch_scc1 .Ls2_done
	s_lshl_b32 s16, s14, 1
	s_mov_b32 s26, 11
	s_mov_b32 s27, 0
	s_mov_b32 s28, 0
	s_mov_b32 s29, 5
	s_cmp_lt_u32 s16, 0x20000
	s_cbranch_scc1 .Ls2_msel
	s_mov_b32 s29, 0
	s_cmp_lt_u32 s16, 0xa0000
	s_cbranch_scc0 .Ls2_m2
	s_sub_u32 s16, s16, 0x20000
	s_mov_b32 s26, 13
	s_mov_b32 s27, 0x480000
	s_mov_b32 s28, 0x12000
	s_branch .Ls2_msel
.Ls2_m2:
	s_sub_u32 s16, s16, 0xa0000
	s_mov_b32 s27, 0x1680000
	s_mov_b32 s28, 0x12900
.Ls2_msel:
	s_lshr_b32 vcc_hi, s29, 2
	v_mul_u32_u24_e32 v4, vcc_hi, v9
	v_mul_u32_u24_e32 v5, vcc_hi, v1
	s_lshr_b32 s17, s16, s26
	s_lshl_b32 s18, s17, s26
	s_sub_u32 s16, s16, s18
	s_and_b32 s25, s17, 1
	s_mul_i32 s17, s17, 36
	s_lshl_b32 s18, s17, s26
	s_add_u32 s18, s18, s27
	s_add_u32 s18, s18, s16
	s_lshl_b32 s19, s17, s29
	s_add_u32 s19, s19, s28
	s_lshl_b32 s0, 4, s29
	s_lshl_b32 s4, 4, s26
	s_lshl_b32 s5, 2, s26
	s_lshl_b32 s16, s18, 2
	s_add_u32 s16, s8, s16
	s_addc_u32 s17, s9, 0
	s_lshl_b32 s20, s19, 2
	s_add_u32 s20, s12, s20
	s_addc_u32 s21, s13, 0
	s_lshl_b32 s19, s18, 1
	s_add_u32 s18, s10, s19
	s_addc_u32 s19, s11, 0
	s_cmp_eq_u32 s25, 1
	s_cbranch_scc1 .Ls2_dir1
	s_mov_b32 s26, s4
	s_mov_b32 s27, 0
	s_mov_b32 s28, s5
	s_mov_b32 s29, 0
	s_mov_b32 s1, 0
	s_mov_b32 s4, 0
	s_mov_b32 s5, 0
	s_mov_b32 s25, 0
	s_branch .Ls2_go
.Ls2_dir1:
	s_mul_i32 s26, s4, 3
	s_add_u32 s16, s16, s26
	s_addc_u32 s17, s17, 0
	s_mul_i32 s26, s5, 3
	s_add_u32 s18, s18, s26
	s_addc_u32 s19, s19, 0
	s_mul_i32 s26, s0, 3
	s_add_u32 s20, s20, s26
	s_addc_u32 s21, s21, 0
	s_sub_u32 s26, 0, s4
	s_mov_b32 s27, -1
	s_sub_u32 s28, 0, s5
	s_mov_b32 s29, -1
	s_mul_i32 s25, s5, 36
	s_mul_i32 s4, s4, 36
	s_mul_i32 s5, s0, 36
	s_sub_u32 s0, 0, s0
	s_mov_b32 s1, -1
.Ls2_go:
	v_mov_b32_e32 v6, 0
	v_mov_b32_e32 v7, 0
	s_mov_b32 vcc_lo, 0
.Ls2_b:
	global_load_dwordx2 v[10:11], v2, s[16:17]
	global_load_dword v46, v4, s[20:21]
	global_load_dword v47, v5, s[20:21]
	s_add_u32 s16, s16, s26
	s_addc_u32 s17, s17, s27
	s_add_u32 s20, s20, s0
	s_addc_u32 s21, s21, s1
	global_load_dwordx2 v[12:13], v2, s[16:17]
	global_load_dword v48, v4, s[20:21]
	global_load_dword v49, v5, s[20:21]
	s_add_u32 s16, s16, s26
	s_addc_u32 s17, s17, s27
	s_add_u32 s20, s20, s0
	s_addc_u32 s21, s21, s1
	global_load_dwordx2 v[14:15], v2, s[16:17]
	global_load_dword v50, v4, s[20:21]
	global_load_dword v51, v5, s[20:21]
	s_add_u32 s16, s16, s26
	s_addc_u32 s17, s17, s27
	s_add_u32 s20, s20, s0
	s_addc_u32 s21, s21, s1
	global_load_dwordx2 v[16:17], v2, s[16:17]
	global_load_dword v52, v4, s[20:21]
	global_load_dword v53, v5, s[20:21]
	s_add_u32 s16, s16, s26
	s_addc_u32 s17, s17, s27
	s_add_u32 s20, s20, s0
	s_addc_u32 s21, s21, s1
	s_add_u32 s16, s16, s4
	s_addc_u32 s17, s17, 0
	s_add_u32 s20, s20, s5
	s_addc_u32 s21, s21, 0
	global_load_dwordx2 v[18:19], v2, s[16:17]
	global_load_dword v54, v4, s[20:21]
	global_load_dword v55, v5, s[20:21]
	s_add_u32 s16, s16, s26
	s_addc_u32 s17, s17, s27
	s_add_u32 s20, s20, s0
	s_addc_u32 s21, s21, s1
	global_load_dwordx2 v[20:21], v2, s[16:17]
	global_load_dword v56, v4, s[20:21]
	global_load_dword v57, v5, s[20:21]
	s_add_u32 s16, s16, s26
	s_addc_u32 s17, s17, s27
	s_add_u32 s20, s20, s0
	s_addc_u32 s21, s21, s1
	global_load_dwordx2 v[22:23], v2, s[16:17]
	global_load_dword v58, v4, s[20:21]
	global_load_dword v59, v5, s[20:21]
	s_add_u32 s16, s16, s26
	s_addc_u32 s17, s17, s27
	s_add_u32 s20, s20, s0
	s_addc_u32 s21, s21, s1
	global_load_dwordx2 v[24:25], v2, s[16:17]
	global_load_dword v60, v4, s[20:21]
	global_load_dword v61, v5, s[20:21]
	s_add_u32 s16, s16, s26
	s_addc_u32 s17, s17, s27
	s_add_u32 s20, s20, s0
	s_addc_u32 s21, s21, s1
	global_load_dwordx2 v[26:27], v2, s[16:17]
	global_load_dword v62, v4, s[20:21]
	global_load_dword v63, v5, s[20:21]
	s_add_u32 s16, s16, s26
	s_addc_u32 s17, s17, s27
	s_add_u32 s20, s20, s0
	s_addc_u32 s21, s21, s1
	global_load_dwordx2 v[28:29], v2, s[16:17]
	global_load_dword v64, v4, s[20:21]
	global_load_dword v65, v5, s[20:21]
	s_add_u32 s16, s16, s26
	s_addc_u32 s17, s17, s27
	s_add_u32 s20, s20, s0
	s_addc_u32 s21, s21, s1
	global_load_dwordx2 v[30:31], v2, s[16:17]
	global_load_dword v66, v4, s[20:21]
	global_load_dword v67, v5, s[20:21]
	s_add_u32 s16, s16, s26
	s_addc_u32 s17, s17, s27
	s_add_u32 s20, s20, s0
	s_addc_u32 s21, s21, s1
	global_load_dwordx2 v[32:33], v2, s[16:17]
	global_load_dword v68, v4, s[20:21]
	global_load_dword v69, v5, s[20:21]
	s_add_u32 s16, s16, s26
	s_addc_u32 s17, s17, s27
	s_add_u32 s20, s20, s0
	s_addc_u32 s21, s21, s1
	global_load_dwordx2 v[34:35], v2, s[16:17]
	global_load_dword v70, v4, s[20:21]
	global_load_dword v71, v5, s[20:21]
	s_add_u32 s16, s16, s26
	s_addc_u32 s17, s17, s27
	s_add_u32 s20, s20, s0
	s_addc_u32 s21, s21, s1
	global_load_dwordx2 v[36:37], v2, s[16:17]
	global_load_dword v72, v4, s[20:21]
	global_load_dword v73, v5, s[20:21]
	s_add_u32 s16, s16, s26
	s_addc_u32 s17, s17, s27
	s_add_u32 s20, s20, s0
	s_addc_u32 s21, s21, s1
	global_load_dwordx2 v[38:39], v2, s[16:17]
	global_load_dword v74, v4, s[20:21]
	global_load_dword v75, v5, s[20:21]
	s_add_u32 s16, s16, s26
	s_addc_u32 s17, s17, s27
	s_add_u32 s20, s20, s0
	s_addc_u32 s21, s21, s1
	global_load_dwordx2 v[40:41], v2, s[16:17]
	global_load_dword v76, v4, s[20:21]
	global_load_dword v77, v5, s[20:21]
	s_add_u32 s16, s16, s26
	s_addc_u32 s17, s17, s27
	s_add_u32 s20, s20, s0
	s_addc_u32 s21, s21, s1
	global_load_dwordx2 v[42:43], v2, s[16:17]
	global_load_dword v78, v4, s[20:21]
	global_load_dword v79, v5, s[20:21]
	s_add_u32 s16, s16, s26
	s_addc_u32 s17, s17, s27
	s_add_u32 s20, s20, s0
	s_addc_u32 s21, s21, s1
	global_load_dwordx2 v[44:45], v2, s[16:17]
	global_load_dword v80, v4, s[20:21]
	global_load_dword v81, v5, s[20:21]
	s_add_u32 s16, s16, s26
	s_addc_u32 s17, s17, s27
	s_add_u32 s20, s20, s0
	s_addc_u32 s21, s21, s1
	s_waitcnt vmcnt(51)
; DEV u16 f2bf(float f) { return (u16)(pack2(f, 0.f) & 0xffffu); }
; __device__ __forceinline__ void ph_scan2(const P& p) {
;     ...
; #pragma unroll
;       for (int u = 0; u < 18; u++) { SIN[aa[u]] = f2bf(run); run = dd[u] * run + loc[u]; }
;     }
; __global__ void __launch_bounds__(NTHR, 2) mega(P p) {
;     ...
;         ph_attn(q, need_ctx, smem);
	v_cvt_pk_bf16_f32 v8, v6, v7
	global_store_dword v3, v8, s[18:19]
	v_fma_f32 v6, v46, v6, v10
	v_fma_f32 v7, v47, v7, v11
	s_add_u32 s18, s18, s28
	s_addc_u32 s19, s19, s29
	s_waitcnt vmcnt(49)
	v_cvt_pk_bf16_f32 v8, v6, v7
	global_store_dword v3, v8, s[18:19]
	v_fma_f32 v6, v48, v6, v12
	v_fma_f32 v7, v49, v7, v13
	s_add_u32 s18, s18, s28
	s_addc_u32 s19, s19, s29
	s_waitcnt vmcnt(47)
	v_cvt_pk_bf16_f32 v8, v6, v7
	global_store_dword v3, v8, s[18:19]
	v_fma_f32 v6, v50, v6, v14
	v_fma_f32 v7, v51, v7, v15
	s_add_u32 s18, s18, s28
	s_addc_u32 s19, s19, s29
	s_waitcnt vmcnt(45)
	v_cvt_pk_bf16_f32 v8, v6, v7
	global_store_dword v3, v8, s[18:19]
	v_fma_f32 v6, v52, v6, v16
	v_fma_f32 v7, v53, v7, v17
	s_add_u32 s18, s18, s28
	s_addc_u32 s19, s19, s29
	s_add_u32 s18, s18, s25
	s_addc_u32 s19, s19, 0
	s_waitcnt vmcnt(43)
	v_cvt_pk_bf16_f32 v8, v6, v7
	global_store_dword v3, v8, s[18:19]
	v_fma_f32 v6, v54, v6, v18
	v_fma_f32 v7, v55, v7, v19
	s_add_u32 s18, s18, s28
	s_addc_u32 s19, s19, s29
	s_waitcnt vmcnt(41)
	v_cvt_pk_bf16_f32 v8, v6, v7
	global_store_dword v3, v8, s[18:19]
	v_fma_f32 v6, v56, v6, v20
	v_fma_f32 v7, v57, v7, v21
	s_add_u32 s18, s18, s28
	s_addc_u32 s19, s19, s29
	s_waitcnt vmcnt(39)
	v_cvt_pk_bf16_f32 v8, v6, v7
	global_store_dword v3, v8, s[18:19]
	v_fma_f32 v6, v58, v6, v22
	v_fma_f32 v7, v59, v7, v23
	s_add_u32 s18, s18, s28
	s_addc_u32 s19, s19, s29
	s_waitcnt vmcnt(37)
	v_cvt_pk_bf16_f32 v8, v6, v7
	global_store_dword v3, v8, s[18:19]
	v_fma_f32 v6, v60, v6, v24
	v_fma_f32 v7, v61, v7, v25
	s_add_u32 s18, s18, s28
	s_addc_u32 s19, s19, s29
	s_waitcnt vmcnt(35)
	v_cvt_pk_bf16_f32 v8, v6, v7
	global_store_dword v3, v8, s[18:19]
	v_fma_f32 v6, v62, v6, v26
	v_fma_f32 v7, v63, v7, v27
	s_add_u32 s18, s18, s28
	s_addc_u32 s19, s19, s29
	s_waitcnt vmcnt(33)
	v_cvt_pk_bf16_f32 v8, v6, v7
	global_store_dword v3, v8, s[18:19]
	v_fma_f32 v6, v64, v6, v28
	v_fma_f32 v7, v65, v7, v29
	s_add_u32 s18, s18, s28
	s_addc_u32 s19, s19, s29
	s_waitcnt vmcnt(31)
	v_cvt_pk_bf16_f32 v8, v6, v7
	global_store_dword v3, v8, s[18:19]
	v_fma_f32 v6, v66, v6, v30
	v_fma_f32 v7, v67, v7, v31
	s_add_u32 s18, s18, s28
	s_addc_u32 s19, s19, s29
	s_waitcnt vmcnt(29)
	v_cvt_pk_bf16_f32 v8, v6, v7
	global_store_dword v3, v8, s[18:19]
	v_fma_f32 v6, v68, v6, v32
	v_fma_f32 v7, v69, v7, v33
	s_add_u32 s18, s18, s28
	s_addc_u32 s19, s19, s29
	s_waitcnt vmcnt(27)
	v_cvt_pk_bf16_f32 v8, v6, v7
	global_store_dword v3, v8, s[18:19]
	v_fma_f32 v6, v70, v6, v34
	v_fma_f32 v7, v71, v7, v35
	s_add_u32 s18, s18, s28
	s_addc_u32 s19, s19, s29
	s_waitcnt vmcnt(25)
	v_cvt_pk_bf16_f32 v8, v6, v7
	global_store_dword v3, v8, s[18:19]
	v_fma_f32 v6, v72, v6, v36
	v_fma_f32 v7, v73, v7, v37
	s_add_u32 s18, s18, s28
	s_addc_u32 s19, s19, s29
	s_waitcnt vmcnt(23)
	v_cvt_pk_bf16_f32 v8, v6, v7
	global_store_dword v3, v8, s[18:19]
	v_fma_f32 v6, v74, v6, v38
	v_fma_f32 v7, v75, v7, v39
	s_add_u32 s18, s18, s28
	s_addc_u32 s19, s19, s29
	s_waitcnt vmcnt(21)
	v_cvt_pk_bf16_f32 v8, v6, v7
	global_store_dword v3, v8, s[18:19]
	v_fma_f32 v6, v76, v6, v40
	v_fma_f32 v7, v77, v7, v41
	s_add_u32 s18, s18, s28
	s_addc_u32 s19, s19, s29
	s_waitcnt vmcnt(19)
	v_cvt_pk_bf16_f32 v8, v6, v7
	global_store_dword v3, v8, s[18:19]
	v_fma_f32 v6, v78, v6, v42
	v_fma_f32 v7, v79, v7, v43
	s_add_u32 s18, s18, s28
	s_addc_u32 s19, s19, s29
	s_waitcnt vmcnt(17)
	v_cvt_pk_bf16_f32 v8, v6, v7
	global_store_dword v3, v8, s[18:19]
	v_fma_f32 v6, v80, v6, v44
	v_fma_f32 v7, v81, v7, v45
	s_add_u32 s18, s18, s28
	s_addc_u32 s19, s19, s29
	s_mov_b32 s4, 0
	s_mov_b32 s5, 0
	s_mov_b32 s25, 0
	s_add_i32 vcc_lo, vcc_lo, 1
	s_cmp_lt_u32 vcc_lo, 2
	s_cbranch_scc1 .Ls2_b
.Ls2_next:
	s_add_i32 s14, s14, s15
	s_branch .Ls2_iter
.Ls2_done:
.LBB0_1239:
	s_or_b64 exec, exec, s[6:7]
	v_readlane_b32 s0, v255, 62
	s_cmp_eq_u32 s0, 2
	s_cbranch_scc1 .LBB0_1262
	s_and_b64 s[0:1], s[40:41], exec
	s_movk_i32 s0, 0x200
	s_mov_b32 s20, 0
	s_cselect_b32 s16, 0x200, s0
	s_add_i32 s17, s20, s87
	v_mov_b32_e32 v196, 0x80
	s_cmp_ge_i32 s17, s16
	s_cbranch_scc1 .LBB0_1262
